# plus P8 and P5 epilogues: the second 128-row half's residual loads requested together with the first half's
# speedup vs baseline: 1.0008x; 1.0008x over previous
.LBB0_2467:
	s_lshl_b32 s1, s28, 6
	v_lshl_add_u32 v154, s0, 8, v143
	s_lshl_b32 s0, s27, 9
	s_or_b32 s0, s1, s0
	v_or_b32_e32 v157, s0, v142
	v_lshl_or_b32 v158, v154, 12, v157
	global_load_dwordx4 v[160:163], v158, s[4:5]
	v_or_b32_e32 v155, 0x100, v158
	global_load_dwordx4 v[164:167], v155, s[4:5]
	v_or_b32_e32 v130, 0x10000, v158
	v_or_b32_e32 v131, 0x10100, v158
	v_or_b32_e32 v132, 0x20000, v158
	v_or_b32_e32 v133, 0x20100, v158
	v_or_b32_e32 v134, 0x30000, v158
	v_or_b32_e32 v156, 0x30100, v158
	global_load_dwordx4 v[150:153], v130, s[4:5]
	global_load_dwordx4 v[146:149], v131, s[4:5]
	global_load_dwordx4 v[142:145], v132, s[4:5]
	global_load_dwordx4 v[138:141], v133, s[4:5]
	s_nop 0
	global_load_dwordx4 v[134:137], v134, s[4:5]
	s_nop 0
	global_load_dwordx4 v[130:133], v156, s[4:5]
	v_add_u32_e32 v232, 0x80000, v158
	v_add_u32_e32 v233, 0x80100, v158
	v_add_u32_e32 v234, 0x90000, v158
	v_add_u32_e32 v235, 0x90100, v158
	v_add_u32_e32 v236, 0xa0000, v158
	v_add_u32_e32 v237, 0xa0100, v158
	v_add_u32_e32 v238, 0xb0000, v158
	v_add_u32_e32 v239, 0xb0100, v158
	global_load_dwordx4 v[200:203], v232, s[4:5]
	global_load_dwordx4 v[204:207], v233, s[4:5]
	global_load_dwordx4 v[208:211], v234, s[4:5]
	global_load_dwordx4 v[212:215], v235, s[4:5]
	global_load_dwordx4 v[216:219], v236, s[4:5]
	global_load_dwordx4 v[220:223], v237, s[4:5]
	global_load_dwordx4 v[224:227], v238, s[4:5]
	global_load_dwordx4 v[228:231], v239, s[4:5]
	v_cmp_eq_u32_e32 vcc, 0, v1
	v_mbcnt_lo_u32_b32 v1, -1, 0
	v_mbcnt_hi_u32_b32 v1, -1, v1
	v_and_b32_e32 v159, 64, v1
	v_xor_b32_e32 v156, 16, v1
	v_add_u32_e32 v159, 64, v159
	v_xor_b32_e32 v168, 32, v1
	v_cmp_lt_i32_e64 s[0:1], v156, v159
	s_mov_b32 s9, 0
	s_waitcnt vmcnt(0)
	v_and_b32_e32 v169, 0xffff0000, v160
	v_cndmask_b32_e64 v156, v1, v156, s[0:1]
	v_cmp_lt_i32_e64 s[0:1], v168, v159
	v_lshlrev_b32_e32 v170, 16, v162
	v_and_b32_e32 v171, 0xffff0000, v162
	v_cndmask_b32_e64 v1, v1, v168, s[0:1]
	v_lshlrev_b32_e32 v168, 16, v160
	v_lshlrev_b32_e32 v160, 16, v161
	v_and_b32_e32 v161, 0xffff0000, v161
	v_lshlrev_b32_e32 v162, 16, v163
	v_and_b32_e32 v163, 0xffff0000, v163
	v_pk_add_f32 v[128:129], v[128:129], v[160:161]
	v_pk_add_f32 v[160:161], v[124:125], v[162:163]
	v_lshlrev_b32_e32 v162, 16, v164
	v_and_b32_e32 v163, 0xffff0000, v164
	v_lshlrev_b32_e32 v164, 16, v165
	v_and_b32_e32 v165, 0xffff0000, v165
	v_pk_add_f32 v[126:127], v[126:127], v[168:169]
	v_lshlrev_b32_e32 v168, 16, v166
	v_and_b32_e32 v169, 0xffff0000, v166
	v_pk_add_f32 v[120:121], v[120:121], v[164:165]
	v_pk_add_f32 v[118:119], v[118:119], v[162:163]
	v_pk_add_f32 v[124:125], v[122:123], v[170:171]
	v_lshlrev_b32_e32 v166, 16, v167
	v_and_b32_e32 v167, 0xffff0000, v167
	v_cvt_pk_bf16_f32 v122, v126, v127
	v_cvt_pk_bf16_f32 v123, v128, v129
	v_mul_f32_e32 v127, v127, v127
	v_mul_f32_e32 v129, v129, v129
	v_pk_add_f32 v[164:165], v[114:115], v[168:169]
	v_mul_f32_e32 v114, v119, v119
	v_mul_f32_e32 v115, v121, v121
	v_mul_f32_e32 v159, v125, v125
	v_pk_add_f32 v[162:163], v[116:117], v[166:167]
	v_fmac_f32_e32 v127, v126, v126
	v_fmac_f32_e32 v129, v128, v128
	v_mul_f32_e32 v116, v165, v165
	v_fmac_f32_e32 v114, v118, v118
	v_fmac_f32_e32 v115, v120, v120
	v_mul_f32_e32 v170, v161, v161
	v_fmac_f32_e32 v159, v124, v124
	v_mul_f32_e32 v117, v163, v163
	v_add_f32_e32 v126, v127, v129
	v_fmac_f32_e32 v116, v164, v164
	v_add_f32_e32 v114, v114, v115
	v_fmac_f32_e32 v170, v160, v160
	v_add_f32_e32 v126, v159, v126
	v_add_f32_e32 v114, v116, v114
	v_fmac_f32_e32 v117, v162, v162
	v_add_f32_e32 v115, v170, v126
	v_add_f32_e32 v114, v117, v114
	v_lshlrev_b32_e32 v156, 2, v156
	v_add_f32_e32 v114, v115, v114
	ds_bpermute_b32 v115, v156, v114
	v_lshlrev_b32_e32 v1, 2, v1
	v_cvt_pk_bf16_f32 v124, v124, v125
	v_cvt_pk_bf16_f32 v125, v160, v161
	v_cvt_pk_bf16_f32 v116, v118, v119
	s_waitcnt lgkmcnt(0)
	v_add_f32_e32 v114, v114, v115
	ds_bpermute_b32 v115, v1, v114
	v_cvt_pk_bf16_f32 v117, v120, v121
	v_cvt_pk_bf16_f32 v118, v164, v165
	v_cvt_pk_bf16_f32 v119, v162, v163
	global_store_dwordx4 v158, v[122:125], s[4:5]
	global_store_dwordx4 v155, v[116:119], s[4:5]
	s_and_saveexec_b64 s[0:1], vcc
	s_cbranch_execz .LBB0_2469
	v_ashrrev_i32_e32 v155, 31, v154
	s_waitcnt lgkmcnt(0)
	v_add_f32_e32 v116, v114, v115
	v_lshlrev_b64 v[114:115], 7, v[154:155]
	v_lshl_add_u64 v[114:115], s[2:3], 0, v[114:115]
	s_lshl_b32 s8, s27, 4
	v_lshl_add_u64 v[114:115], v[114:115], 0, s[8:9]
	s_lshl_b32 s8, s28, 2
	v_lshl_add_u64 v[114:115], v[114:115], 0, s[8:9]
	global_store_dword v[114:115], v116, off

.LBB0_2475:
	s_or_b64 exec, exec, s[0:1]
	v_add_u32_e32 v66, 0x80000, v158
	v_mov_b64_e32 v[92:93], v[200:201]
	v_mov_b64_e32 v[94:95], v[202:203]
	v_add_u32_e32 v66, 0x80100, v158
	v_mov_b64_e32 v[96:97], v[204:205]
	v_mov_b64_e32 v[98:99], v[206:207]
	v_add_u32_e32 v90, 0x90000, v158
	v_add_u32_e32 v91, 0x90100, v158
	v_add_u32_e32 v100, 0xa0000, v158
	v_add_u32_e32 v101, 0xa0100, v158
	v_add_u32_e32 v102, 0xb0000, v158
	v_add_u32_e32 v103, 0xb0100, v158
	v_mov_b64_e32 v[86:87], v[208:209]
	v_mov_b64_e32 v[88:89], v[210:211]
	v_mov_b64_e32 v[82:83], v[212:213]
	v_mov_b64_e32 v[84:85], v[214:215]
	v_mov_b64_e32 v[78:79], v[216:217]
	v_mov_b64_e32 v[80:81], v[218:219]
	v_mov_b64_e32 v[74:75], v[220:221]
	v_mov_b64_e32 v[76:77], v[222:223]
	v_mov_b64_e32 v[70:71], v[224:225]
	v_mov_b64_e32 v[72:73], v[226:227]
	s_waitcnt lgkmcnt(0)
	v_mov_b64_e32 v[66:67], v[228:229]
	v_mov_b64_e32 v[68:69], v[230:231]
	v_add_u32_e32 v90, 0x80, v154
	v_lshl_or_b32 v91, v90, 12, v157
	s_waitcnt vmcnt(7)
	v_lshlrev_b32_e32 v100, 16, v92
	v_and_b32_e32 v101, 0xffff0000, v92
	v_lshlrev_b32_e32 v92, 16, v93
	v_and_b32_e32 v93, 0xffff0000, v93
	s_waitcnt vmcnt(6)
	v_lshlrev_b32_e32 v104, 16, v96
	v_and_b32_e32 v105, 0xffff0000, v96
	v_lshlrev_b32_e32 v96, 16, v97
	v_and_b32_e32 v97, 0xffff0000, v97
	v_lshlrev_b32_e32 v102, 16, v94
	v_and_b32_e32 v103, 0xffff0000, v94
	v_lshlrev_b32_e32 v94, 16, v95
	v_and_b32_e32 v95, 0xffff0000, v95
	v_lshlrev_b32_e32 v106, 16, v98
	v_and_b32_e32 v107, 0xffff0000, v98
	v_lshlrev_b32_e32 v98, 16, v99
	v_and_b32_e32 v99, 0xffff0000, v99
	v_pk_add_f32 v[64:65], v[64:65], v[92:93]
	v_pk_add_f32 v[62:63], v[62:63], v[100:101]
	v_pk_add_f32 v[56:57], v[56:57], v[96:97]
	v_pk_add_f32 v[54:55], v[54:55], v[104:105]
	v_pk_add_f32 v[60:61], v[60:61], v[94:95]
	v_pk_add_f32 v[58:59], v[58:59], v[102:103]
	v_pk_add_f32 v[92:93], v[52:53], v[98:99]
	v_pk_add_f32 v[94:95], v[50:51], v[106:107]
	v_cvt_pk_bf16_f32 v50, v62, v63
	v_mul_f32_e32 v53, v63, v63
	v_mul_f32_e32 v63, v65, v65
	v_mul_f32_e32 v96, v55, v55
	v_mul_f32_e32 v97, v57, v57
	v_cvt_pk_bf16_f32 v52, v58, v59
	v_mul_f32_e32 v59, v59, v59
	v_mul_f32_e32 v98, v95, v95
	v_fmac_f32_e32 v53, v62, v62
	v_fmac_f32_e32 v63, v64, v64
	v_fmac_f32_e32 v96, v54, v54
	v_fmac_f32_e32 v97, v56, v56
	v_cvt_pk_bf16_f32 v51, v64, v65
	v_mul_f32_e32 v65, v61, v61
	v_mul_f32_e32 v99, v93, v93
	v_fmac_f32_e32 v59, v58, v58
	v_fmac_f32_e32 v98, v94, v94
	v_add_f32_e32 v53, v53, v63
	v_add_f32_e32 v58, v96, v97
	v_fmac_f32_e32 v65, v60, v60
	v_fmac_f32_e32 v99, v92, v92
	v_add_f32_e32 v53, v59, v53
	v_add_f32_e32 v58, v98, v58
	v_add_f32_e32 v53, v65, v53
	v_add_f32_e32 v58, v99, v58
	v_add_f32_e32 v58, v53, v58
	ds_bpermute_b32 v59, v156, v58
	v_cvt_pk_bf16_f32 v53, v60, v61
	global_store_dwordx4 v91, v[50:53], s[4:5]
	s_waitcnt lgkmcnt(0)
	s_nop 0
	v_add_f32_e32 v50, v58, v59
	ds_bpermute_b32 v51, v1, v50
	v_cvt_pk_bf16_f32 v52, v54, v55
	v_cvt_pk_bf16_f32 v53, v56, v57
	v_cvt_pk_bf16_f32 v54, v94, v95
	v_cvt_pk_bf16_f32 v55, v92, v93
	v_or_b32_e32 v56, 0x100, v91
	global_store_dwordx4 v56, v[52:55], s[4:5]
	s_and_saveexec_b64 s[0:1], vcc
	s_cbranch_execz .LBB0_2477
	v_ashrrev_i32_e32 v91, 31, v90
	s_waitcnt lgkmcnt(0)
	v_add_f32_e32 v52, v50, v51
	v_lshlrev_b64 v[50:51], 7, v[90:91]
	v_lshl_add_u64 v[50:51], s[2:3], 0, v[50:51]
	s_lshl_b32 s8, s27, 4
	v_lshl_add_u64 v[50:51], v[50:51], 0, s[8:9]
	s_lshl_b32 s8, s28, 2
	v_lshl_add_u64 v[50:51], v[50:51], 0, s[8:9]
	global_store_dword v[50:51], v52, off

.LBB0_2801:
	s_lshl_b32 s18, s11, 8
	s_add_i32 s1, s18, s43
	s_lshl_b32 s0, s36, 5
	v_or_b32_e32 v158, s1, v1
	s_lshl_b32 s1, s35, 8
	s_or_b32 s0, s1, s0
	v_or_b32_e32 v156, s0, v154
	v_ashrrev_i32_e32 v157, 31, v156
	v_ashrrev_i32_e32 v159, 31, v158
	v_lshl_add_u64 v[160:161], v[156:157], 1, s[6:7]
	v_lshlrev_b64 v[130:131], 12, v[158:159]
	v_lshl_add_u64 v[130:131], v[160:161], 0, v[130:131]
	s_barrier
	global_load_dwordx4 v[164:167], v[130:131], off
	global_load_dwordx4 v[168:171], v[130:131], off offset:256
	v_or_b32_e32 v130, 16, v158
	v_or_b32_e32 v132, 32, v158
	v_or_b32_e32 v134, 48, v158
	v_ashrrev_i32_e32 v131, 31, v130
	v_ashrrev_i32_e32 v133, 31, v132
	v_ashrrev_i32_e32 v135, 31, v134
	v_lshlrev_b64 v[130:131], 12, v[130:131]
	v_lshlrev_b64 v[132:133], 12, v[132:133]
	v_lshlrev_b64 v[134:135], 12, v[134:135]
	v_lshl_add_u64 v[130:131], v[160:161], 0, v[130:131]
	v_lshl_add_u64 v[132:133], v[160:161], 0, v[132:133]
	v_lshl_add_u64 v[172:173], v[160:161], 0, v[134:135]
	global_load_dwordx4 v[150:153], v[130:131], off
	global_load_dwordx4 v[146:149], v[130:131], off offset:256
	global_load_dwordx4 v[142:145], v[132:133], off
	global_load_dwordx4 v[138:141], v[132:133], off offset:256
	global_load_dwordx4 v[134:137], v[172:173], off
	s_nop 0
	global_load_dwordx4 v[130:133], v[172:173], off offset:256
	v_lshlrev_b64 v[232:233], 12, v[158:159]
	v_lshl_add_u64 v[232:233], v[160:161], 0, v[232:233]
	s_mov_b64 vcc, 0x80000
	s_nop 1
	v_lshl_add_u64 v[232:233], v[232:233], 0, vcc
	s_mov_b64 vcc, 0x10000
	s_nop 1
	v_lshl_add_u64 v[234:235], v[232:233], 0, vcc
	v_lshl_add_u64 v[236:237], v[234:235], 0, vcc
	v_lshl_add_u64 v[238:239], v[236:237], 0, vcc
	global_load_dwordx4 v[200:203], v[232:233], off
	global_load_dwordx4 v[204:207], v[232:233], off offset:256
	global_load_dwordx4 v[208:211], v[234:235], off
	global_load_dwordx4 v[212:215], v[234:235], off offset:256
	global_load_dwordx4 v[216:219], v[236:237], off
	global_load_dwordx4 v[220:223], v[236:237], off offset:256
	global_load_dwordx4 v[224:227], v[238:239], off
	global_load_dwordx4 v[228:231], v[238:239], off offset:256
	v_mbcnt_lo_u32_b32 v163, -1, 0
	v_mbcnt_hi_u32_b32 v180, -1, v163
	v_and_b32_e32 v172, 64, v180
	v_add_u32_e32 v181, 64, v172
	v_xor_b32_e32 v163, 16, v180
	v_cmp_lt_i32_e32 vcc, v163, v181
	s_lshl_b32 s2, s36, 2
	s_add_i32 s4, s2, 0
	v_cndmask_b32_e32 v163, v180, v163, vcc
	v_lshlrev_b32_e32 v163, 2, v163
	v_cmp_gt_u32_e64 s[0:1], 16, v198
	s_add_i32 s4, s4, 0x22800
	s_waitcnt vmcnt(0)
	v_lshlrev_b32_e32 v172, 16, v164
	v_and_b32_e32 v173, 0xffff0000, v164
	v_lshlrev_b32_e32 v164, 16, v165
	v_and_b32_e32 v165, 0xffff0000, v165
	v_lshlrev_b32_e32 v176, 16, v168
	v_and_b32_e32 v177, 0xffff0000, v168
	v_lshlrev_b32_e32 v168, 16, v169
	v_and_b32_e32 v169, 0xffff0000, v169
	v_lshlrev_b32_e32 v174, 16, v166
	v_and_b32_e32 v175, 0xffff0000, v166
	v_lshlrev_b32_e32 v178, 16, v170
	v_and_b32_e32 v179, 0xffff0000, v170
	v_pk_add_f32 v[128:129], v[128:129], v[164:165]
	v_pk_add_f32 v[126:127], v[126:127], v[172:173]
	v_pk_add_f32 v[120:121], v[120:121], v[168:169]
	v_pk_add_f32 v[118:119], v[118:119], v[176:177]
	v_lshlrev_b32_e32 v166, 16, v167
	v_and_b32_e32 v167, 0xffff0000, v167
	v_lshlrev_b32_e32 v170, 16, v171
	v_and_b32_e32 v171, 0xffff0000, v171
	v_pk_add_f32 v[122:123], v[122:123], v[174:175]
	v_pk_add_f32 v[114:115], v[114:115], v[178:179]
	v_mul_f32_e32 v164, v127, v127
	v_mul_f32_e32 v165, v129, v129
	v_mul_f32_e32 v168, v119, v119
	v_mul_f32_e32 v169, v121, v121
	v_pk_add_f32 v[124:125], v[124:125], v[166:167]
	v_pk_add_f32 v[116:117], v[116:117], v[170:171]
	v_mul_f32_e32 v166, v123, v123
	v_mul_f32_e32 v170, v115, v115
	v_fmac_f32_e32 v164, v126, v126
	v_fmac_f32_e32 v165, v128, v128
	v_fmac_f32_e32 v168, v118, v118
	v_fmac_f32_e32 v169, v120, v120
	v_mul_f32_e32 v167, v125, v125
	v_mul_f32_e32 v171, v117, v117
	v_fmac_f32_e32 v166, v122, v122
	v_fmac_f32_e32 v170, v114, v114
	v_add_f32_e32 v164, v164, v165
	v_add_f32_e32 v165, v168, v169
	v_fmac_f32_e32 v167, v124, v124
	v_fmac_f32_e32 v171, v116, v116
	v_add_f32_e32 v164, v166, v164
	v_add_f32_e32 v165, v170, v165
	v_add_f32_e32 v164, v167, v164
	v_add_f32_e32 v165, v171, v165
	v_add_f32_e32 v165, v164, v165
	ds_bpermute_b32 v166, v163, v165
	v_xor_b32_e32 v164, 32, v180
	v_cmp_lt_i32_e32 vcc, v164, v181
	s_waitcnt lgkmcnt(0)
	v_add_f32_e32 v165, v165, v166
	v_cndmask_b32_e32 v164, v180, v164, vcc
	v_lshlrev_b32_e32 v164, 2, v164
	ds_bpermute_b32 v166, v164, v165
	s_and_saveexec_b64 s[2:3], s[0:1]
	s_cbranch_execz .LBB0_2803
	s_waitcnt lgkmcnt(0)
	v_add_f32_e32 v165, v165, v166
	v_lshl_add_u32 v166, v155, 4, s4
	ds_write_b32 v166, v165

.LBB0_2809:
	s_or_b64 exec, exec, s[2:3]
	s_waitcnt lgkmcnt(0)
	v_lshlrev_b64 v[66:67], 12, v[158:159]
	v_lshl_add_u64 v[66:67], v[160:161], 0, v[66:67]
	v_add_co_u32_e32 v68, vcc, 0x80000, v66
	s_mov_b64 s[2:3], 0x80000
	s_nop 0
	v_addc_co_u32_e32 v69, vcc, 0, v67, vcc
	v_mov_b64_e32 v[158:159], v[200:201]
	v_mov_b64_e32 v[160:161], v[202:203]
	v_lshl_add_u64 v[68:69], v[66:67], 0, s[2:3]
	v_mov_b64_e32 v[166:167], v[204:205]
	v_mov_b64_e32 v[168:169], v[206:207]
	v_add_co_u32_e32 v72, vcc, 0x90000, v66
	s_mov_b64 s[2:3], 0x90000
	s_nop 0
	v_addc_co_u32_e32 v73, vcc, 0, v67, vcc
	v_add_co_u32_e32 v74, vcc, 0xa0000, v66
	s_mov_b64 s[14:15], 0xa0000
	s_mov_b64 s[16:17], 0xb0000
	v_addc_co_u32_e32 v75, vcc, 0, v67, vcc
	v_lshl_add_u64 v[68:69], v[66:67], 0, s[2:3]
	v_lshl_add_u64 v[70:71], v[66:67], 0, s[14:15]
	v_lshl_add_u64 v[170:171], v[66:67], 0, s[16:17]
	v_add_co_u32_e32 v66, vcc, 0xb0000, v66
	v_mov_b64_e32 v[86:87], v[208:209]
	v_mov_b64_e32 v[88:89], v[210:211]
	v_mov_b64_e32 v[82:83], v[212:213]
	v_mov_b64_e32 v[84:85], v[214:215]
	v_addc_co_u32_e32 v67, vcc, 0, v67, vcc
	v_mov_b64_e32 v[78:79], v[216:217]
	v_mov_b64_e32 v[80:81], v[218:219]
	s_nop 0
	v_mov_b64_e32 v[74:75], v[220:221]
	v_mov_b64_e32 v[76:77], v[222:223]
	s_nop 0
	v_mov_b64_e32 v[70:71], v[224:225]
	v_mov_b64_e32 v[72:73], v[226:227]
	s_nop 0
	v_mov_b64_e32 v[66:67], v[228:229]
	v_mov_b64_e32 v[68:69], v[230:231]
	s_waitcnt vmcnt(7)
	v_lshlrev_b32_e32 v170, 16, v158
	v_and_b32_e32 v171, 0xffff0000, v158
	v_lshlrev_b32_e32 v158, 16, v159
	v_and_b32_e32 v159, 0xffff0000, v159
	s_waitcnt vmcnt(6)
	v_lshlrev_b32_e32 v174, 16, v166
	v_and_b32_e32 v175, 0xffff0000, v166
	v_lshlrev_b32_e32 v166, 16, v167
	v_and_b32_e32 v167, 0xffff0000, v167
	v_lshlrev_b32_e32 v172, 16, v160
	v_and_b32_e32 v173, 0xffff0000, v160
	v_lshlrev_b32_e32 v176, 16, v168
	v_and_b32_e32 v177, 0xffff0000, v168
	v_pk_add_f32 v[64:65], v[64:65], v[158:159]
	v_pk_add_f32 v[62:63], v[62:63], v[170:171]
	v_pk_add_f32 v[56:57], v[56:57], v[166:167]
	v_pk_add_f32 v[54:55], v[54:55], v[174:175]
	v_lshlrev_b32_e32 v160, 16, v161
	v_and_b32_e32 v161, 0xffff0000, v161
	v_lshlrev_b32_e32 v168, 16, v169
	v_and_b32_e32 v169, 0xffff0000, v169
	v_pk_add_f32 v[58:59], v[58:59], v[172:173]
	v_pk_add_f32 v[50:51], v[50:51], v[176:177]
	v_mul_f32_e32 v158, v63, v63
	v_mul_f32_e32 v159, v65, v65
	v_mul_f32_e32 v165, v55, v55
	v_mul_f32_e32 v166, v57, v57
	v_pk_add_f32 v[60:61], v[60:61], v[160:161]
	v_pk_add_f32 v[52:53], v[52:53], v[168:169]
	v_mul_f32_e32 v160, v59, v59
	v_mul_f32_e32 v167, v51, v51
	v_fmac_f32_e32 v158, v62, v62
	v_fmac_f32_e32 v159, v64, v64
	v_fmac_f32_e32 v165, v54, v54
	v_fmac_f32_e32 v166, v56, v56
	v_mul_f32_e32 v161, v61, v61
	v_mul_f32_e32 v168, v53, v53
	v_fmac_f32_e32 v160, v58, v58
	v_fmac_f32_e32 v167, v50, v50
	v_add_f32_e32 v158, v158, v159
	v_add_f32_e32 v159, v165, v166
	v_fmac_f32_e32 v161, v60, v60
	v_fmac_f32_e32 v168, v52, v52
	v_add_f32_e32 v158, v160, v158
	v_add_f32_e32 v159, v167, v159
	v_add_f32_e32 v158, v161, v158
	v_add_f32_e32 v159, v168, v159
	v_add_f32_e32 v158, v158, v159
	ds_bpermute_b32 v159, v163, v158
	s_waitcnt lgkmcnt(0)
	v_add_f32_e32 v158, v158, v159
	ds_bpermute_b32 v159, v164, v158
	s_and_saveexec_b64 s[2:3], s[0:1]
	s_cbranch_execz .LBB0_2811
	s_waitcnt lgkmcnt(0)
	v_add_f32_e32 v158, v158, v159
	v_lshl_add_u32 v159, v155, 4, s4
	ds_write_b32 v159, v158 offset:2048
